# prompt-group P4 rebalance (state-chain workgroups take no attention unit, the others 4) on top of v21
# speedup vs baseline: 1.0245x; 1.0031x over previous
.LBB0_729:
	s_add_i32 s76, s76, 1
	s_cmp_eq_u32 s76, 4
	v_readlane_b32 s92, v254, 33
	s_barrier
	s_cbranch_scc1 .LBB0_756
.LBB0_730:
	v_readlane_b32 s0, v253, 56
	s_lshl_b32 s0, s0, 2
	s_addk_i32 s0, 0xfe00
	s_add_i32 s0, s0, s76
	v_mov_b32_e32 v19, v172
	s_and_b32 s2, s0, 3
	s_ashr_i32 s0, s0, 2
	v_readlane_b32 s1, v254, 25
	s_and_b32 s6, s0, s92
	s_ashr_i32 s0, s0, s1
	v_ashrrev_i32_e32 v16, 7, v19
	s_ashr_i32 s1, s0, 31
	v_lshl_add_u32 v18, s2, 2, v16
	v_lshrrev_b32_e32 v16, 5, v19
	s_lshl_b64 s[0:1], s[0:1], 12
	v_and_b32_e32 v229, 2, v16
	s_lshl_b32 s5, s6, 7
	v_lshlrev_b32_e32 v16, 6, v18
	v_and_b32_e32 v228, 31, v19
	s_add_u32 s33, s0, s5
	v_ashrrev_i32_e32 v17, 31, v16
	v_bfe_u32 v26, v19, 5, 1
	s_addc_u32 s77, s1, 0
	v_lshlrev_b64 v[20:21], 1, v[16:17]
	v_lshl_or_b32 v27, v229, 5, v228
	v_lshl_add_u64 v[16:17], s[82:83], 0, v[20:21]
	v_lshlrev_b32_e32 v22, 4, v26
	v_mov_b32_e32 v23, v175
	v_or_b32_e32 v24, s33, v27
	v_mov_b32_e32 v25, s77
	v_lshl_add_u64 v[22:23], v[16:17], 0, v[22:23]
	v_lshl_add_u64 v[20:21], s[86:87], 0, v[20:21]
	v_lshlrev_b64 v[28:29], 11, v[24:25]
	v_or_b32_e32 v24, s5, v27
	v_or_b32_e32 v27, 32, v27
	v_lshlrev_b32_e32 v174, 3, v26
	v_lshl_add_u64 v[30:31], v[22:23], 0, v[28:29]
	v_lshlrev_b32_e32 v32, 4, v24
	v_mov_b32_e32 v33, v175
	v_lshl_add_u64 v[28:29], v[20:21], 0, v[28:29]
	v_or_b32_e32 v24, s33, v27
	v_lshl_add_u64 v[32:33], v[32:33], 2, s[84:85]
	v_lshl_add_u64 v[28:29], v[28:29], 0, v[174:175]
	v_lshlrev_b64 v[24:25], 11, v[24:25]
	v_or_b32_e32 v27, s5, v27
	global_load_dwordx4 v[92:95], v[32:33], off offset:48
	global_load_dwordx4 v[96:99], v[32:33], off offset:32
	global_load_dwordx4 v[100:103], v[32:33], off offset:16
	global_load_dwordx4 v[104:107], v[32:33], off
	global_load_dwordx4 v[108:111], v[30:31], off
	global_load_dwordx4 v[112:115], v[30:31], off offset:32
	global_load_dwordx4 v[116:119], v[30:31], off offset:64
	global_load_dwordx4 v[120:123], v[30:31], off offset:96
	global_load_dwordx2 v[184:185], v[28:29], off
	global_load_dwordx2 v[186:187], v[28:29], off offset:16
	global_load_dwordx2 v[188:189], v[28:29], off offset:32
	global_load_dwordx2 v[190:191], v[28:29], off offset:48
	global_load_dwordx2 v[192:193], v[28:29], off offset:64
	global_load_dwordx2 v[194:195], v[28:29], off offset:80
	global_load_dwordx2 v[196:197], v[28:29], off offset:96
	global_load_dwordx2 v[198:199], v[28:29], off offset:112
	v_lshlrev_b32_e32 v28, 4, v27
	v_mov_b32_e32 v29, v175
	v_lshl_add_u64 v[20:21], v[20:21], 0, v[24:25]
	v_lshl_add_u64 v[28:29], v[28:29], 2, s[84:85]
	v_lshl_add_u64 v[20:21], v[20:21], 0, v[174:175]
	v_lshl_add_u64 v[22:23], v[22:23], 0, v[24:25]
	global_load_dwordx4 v[124:127], v[28:29], off offset:48
	global_load_dwordx4 v[128:131], v[28:29], off offset:32
	global_load_dwordx4 v[132:135], v[28:29], off offset:16
	global_load_dwordx4 v[136:139], v[28:29], off
	global_load_dwordx4 v[140:143], v[22:23], off
	global_load_dwordx4 v[144:147], v[22:23], off offset:32
	global_load_dwordx4 v[148:151], v[22:23], off offset:64
	global_load_dwordx4 v[152:155], v[22:23], off offset:96
	global_load_dwordx2 v[200:201], v[20:21], off
	global_load_dwordx2 v[202:203], v[20:21], off offset:16
	global_load_dwordx2 v[204:205], v[20:21], off offset:32
	global_load_dwordx2 v[206:207], v[20:21], off offset:48
	global_load_dwordx2 v[208:209], v[20:21], off offset:64
	global_load_dwordx2 v[210:211], v[20:21], off offset:80
	global_load_dwordx2 v[212:213], v[20:21], off offset:96
	global_load_dwordx2 v[214:215], v[20:21], off offset:112
	s_addk_i32 s5, 0xff80
	v_and_b32_e32 v20, 7, v19
	v_ashrrev_i32_e32 v21, 3, v19
	s_lshl_b32 s4, s2, 6
	v_lshlrev_b32_e32 v22, 3, v20
	v_add_u32_e32 v24, s5, v21
	v_readlane_b32 s2, v254, 7
	v_lshl_add_u32 v20, v20, 4, 0
	v_lshlrev_b32_e32 v22, 1, v22
	v_cmp_gt_u32_e32 vcc, s2, v24
	s_and_saveexec_b64 s[2:3], vcc
	s_cbranch_execz .LBB0_732
	v_mov_b32_e32 v25, v175
	v_lshl_add_u64 v[24:25], s[0:1], 0, v[24:25]
	v_lshlrev_b64 v[24:25], 9, v[24:25]
	v_readlane_b32 s12, v253, 3
	v_lshl_add_u64 v[24:25], s[88:89], 0, v[24:25]
	s_lshl_b32 s8, s4, 1
	s_mov_b32 s9, s12
	v_lshl_add_u64 v[24:25], v[24:25], 0, s[8:9]
	v_mov_b32_e32 v23, v175
	v_lshl_add_u64 v[24:25], v[24:25], 0, v[22:23]
	global_load_dwordx4 v[28:31], v[24:25], off
	s_movk_i32 s7, 0x90
	v_mad_u64_u32 v[24:25], s[8:9], v21, s7, v[20:21]
	v_readlane_b32 s13, v253, 4
	v_readlane_b32 s14, v253, 5
	v_readlane_b32 s15, v253, 6
	v_readlane_b32 s16, v253, 7
	v_readlane_b32 s17, v253, 8
	v_readlane_b32 s18, v253, 9
	v_readlane_b32 s19, v253, 10
	v_readlane_b32 s20, v253, 11
	v_readlane_b32 s21, v253, 12
	v_readlane_b32 s22, v253, 13
	v_readlane_b32 s23, v253, 14
	v_readlane_b32 s24, v253, 15
	v_readlane_b32 s25, v253, 16
	v_readlane_b32 s26, v253, 17
	v_readlane_b32 s27, v253, 18
	s_waitcnt vmcnt(0)
	ds_write_b128 v24, v[28:31]
